# MLA software pipelining across the tile barrier: second block's P*V MFMA chain deferred to the next tile start (runs while the first block's K fragments are read from LDS)
# baseline (speedup 1.0000x reference)
; DI unsigned pk2(float lo, float hi) { typedef float v2f __attribute__((ext_vector_type(2))); typedef __bf16 v2b __attribute__((ext_vector_type(2))); v2f v = {lo, hi}; v2b b = __builtin_convertvector(v, v2b); return __builtin_bit_cast(unsigned, b); }
; #define MFMA32(a, b, c) __builtin_amdgcn_mfma_f32_32x32x16_bf16((a), (b), (c), 0, 0, 0)
; DI float xhalf_sum(float m) { auto rr = __builtin_amdgcn_permlane32_swap(__float_as_uint(m), __float_as_uint(m), false, false); return __uint_as_float(rr[0]) + __uint_as_float(rr[1]); }
; template <int DQK, int DV, bool CAUSAL, int KT, bool PRIO>
; DI void attn_unit(const bf16_t* Qb, int qpitch, const bf16_t* Kb, int kpitch, const bf16_t* Vtb, int vpitch, bf16_t* Ob, int opitch, int q0, int nt, LAS unsigned char* lds, float kbound, const float* qgain, const int* qpos, float qscale) {
;     ...
;                     for (int q4 = 0; q4 < 4; ++q4)
; #pragma unroll
;                         for (int d = 0; d < NDB; ++d) o[d] = MFMA32(vf[q4][d], pf[q4], o[d]);
;                     __builtin_amdgcn_sched_barrier(0); __builtin_amdgcn_s_setprio(0); __builtin_amdgcn_sched_barrier(0);
;     ...
;     lrun = xhalf_sum(lrun);
;     const float inv = 1.0f / lrun;
;     bf16_t* orow = Ob + (size_t)(32 * w + r) * opitch;
; #pragma unroll
;     for (int d = 0; d < DV / 32; ++d)
; #pragma unroll
;         for (int g = 0; g < 4; ++g) { u32x2 wv; wv.x = pk2(o[d][4 * g] * inv, o[d][4 * g + 1] * inv); wv.y = pk2(o[d][4 * g + 2] * inv, o[d][4 * g + 3] * inv);
;             *(u32x2*)(orow + 32 * d + 8 * g + 4 * h) = wv; }
.LBB0_1479:
	s_cmp_eq_u32 s98, 0
	s_cbranch_scc1 .Lmla_dpvc
	s_setprio 1
	v_mfma_f32_32x32x16_bf16 v[32:47], v[156:159], v[64:67], v[32:47]
	v_mfma_f32_32x32x16_bf16 v[16:31], v[152:155], v[64:67], v[16:31]
	v_mfma_f32_32x32x16_bf16 v[32:47], v[140:143], v[72:75], v[32:47]
	v_mfma_f32_32x32x16_bf16 v[16:31], v[148:151], v[72:75], v[16:31]
	v_mfma_f32_32x32x16_bf16 v[32:47], v[144:147], v[68:71], v[32:47]
	v_mfma_f32_32x32x16_bf16 v[16:31], v[10:13], v[68:71], v[16:31]
	v_mfma_f32_32x32x16_bf16 v[32:47], v[6:9], v[76:79], v[32:47]
	v_mfma_f32_32x32x16_bf16 v[16:31], v[2:5], v[76:79], v[16:31]
	s_setprio 0
	s_mov_b32 s98, 0
	s_nop 0
	s_nop 0

; DI float xhalf_sum(float m) { auto rr = __builtin_amdgcn_permlane32_swap(__float_as_uint(m), __float_as_uint(m), false, false); return __uint_as_float(rr[0]) + __uint_as_float(rr[1]); }
; template <int DQK, int DV, bool CAUSAL, int KT, bool PRIO>
; DI void attn_unit(const bf16_t* Qb, int qpitch, const bf16_t* Kb, int kpitch, const bf16_t* Vtb, int vpitch, bf16_t* Ob, int opitch, int q0, int nt, LAS unsigned char* lds, float kbound, const float* qgain, const int* qpos, float qscale) {
;     ...
;     if (PRIO) {
;         float q2 = 0.f;
; #pragma unroll
;         for (int ks = 0; ks < DQK / 16; ++ks)
; #pragma unroll
;             for (int e = 0; e < 8; ++e) { const float v = __uint_as_float(((unsigned)(unsigned short)qf[ks][e]) << 16); q2 += v * v; }
;         q2 = xhalf_sum(q2);
;         nomax = __all(sqrtf(q2) * kbound <= 100.0f) != 0;
.LBB0_1486:
	s_waitcnt vmcnt(0) lgkmcnt(0)
	v_and_b32_e32 v9, 0xffff0000, v116
	v_lshlrev_b32_e32 v8, 16, v116
	v_mul_f32_e32 v11, v9, v9
	v_fmac_f32_e32 v11, v8, v8
	v_lshlrev_b32_e32 v8, 16, v117
	v_fmac_f32_e32 v11, v8, v8
	v_and_b32_e32 v8, 0xffff0000, v117
	v_fmac_f32_e32 v11, v8, v8
	v_lshlrev_b32_e32 v8, 16, v118
	v_fmac_f32_e32 v11, v8, v8
	v_and_b32_e32 v8, 0xffff0000, v118
	v_fmac_f32_e32 v11, v8, v8
	v_lshlrev_b32_e32 v8, 16, v119
	v_fmac_f32_e32 v11, v8, v8
	v_and_b32_e32 v8, 0xffff0000, v119
	v_fmac_f32_e32 v11, v8, v8
	v_lshlrev_b32_e32 v8, 16, v120
	v_fmac_f32_e32 v11, v8, v8
	v_and_b32_e32 v8, 0xffff0000, v120
	v_fmac_f32_e32 v11, v8, v8
	v_lshlrev_b32_e32 v8, 16, v121
	v_fmac_f32_e32 v11, v8, v8
	v_and_b32_e32 v8, 0xffff0000, v121
	v_fmac_f32_e32 v11, v8, v8
	v_lshlrev_b32_e32 v8, 16, v122
	v_fmac_f32_e32 v11, v8, v8
	v_and_b32_e32 v8, 0xffff0000, v122
	v_fmac_f32_e32 v11, v8, v8
	v_lshlrev_b32_e32 v8, 16, v123
	v_fmac_f32_e32 v11, v8, v8
	v_and_b32_e32 v8, 0xffff0000, v123
	v_fmac_f32_e32 v11, v8, v8
	v_lshlrev_b32_e32 v8, 16, v124
	v_fmac_f32_e32 v11, v8, v8
	v_and_b32_e32 v8, 0xffff0000, v124
	v_fmac_f32_e32 v11, v8, v8
	v_lshlrev_b32_e32 v8, 16, v125
	v_fmac_f32_e32 v11, v8, v8
	v_and_b32_e32 v8, 0xffff0000, v125
	v_fmac_f32_e32 v11, v8, v8
	v_lshlrev_b32_e32 v8, 16, v126
	v_fmac_f32_e32 v11, v8, v8
	v_and_b32_e32 v8, 0xffff0000, v126
	v_fmac_f32_e32 v11, v8, v8
	v_lshlrev_b32_e32 v8, 16, v127
	v_fmac_f32_e32 v11, v8, v8
	v_and_b32_e32 v8, 0xffff0000, v127
	v_fmac_f32_e32 v11, v8, v8
	v_lshlrev_b32_e32 v8, 16, v128
	v_fmac_f32_e32 v11, v8, v8
	v_and_b32_e32 v8, 0xffff0000, v128
	v_fmac_f32_e32 v11, v8, v8
	v_lshlrev_b32_e32 v8, 16, v129
	v_fmac_f32_e32 v11, v8, v8
	v_and_b32_e32 v8, 0xffff0000, v129
	v_fmac_f32_e32 v11, v8, v8
	v_lshlrev_b32_e32 v8, 16, v130
	v_fmac_f32_e32 v11, v8, v8
	v_and_b32_e32 v8, 0xffff0000, v130
	v_fmac_f32_e32 v11, v8, v8
	v_lshlrev_b32_e32 v8, 16, v131
	v_fmac_f32_e32 v11, v8, v8
	v_and_b32_e32 v8, 0xffff0000, v131
	v_fmac_f32_e32 v11, v8, v8
	v_lshlrev_b32_e32 v8, 16, v132
	v_fmac_f32_e32 v11, v8, v8
	v_and_b32_e32 v8, 0xffff0000, v132
	v_fmac_f32_e32 v11, v8, v8
	v_lshlrev_b32_e32 v8, 16, v133
	v_fmac_f32_e32 v11, v8, v8
	v_and_b32_e32 v8, 0xffff0000, v133
	v_fmac_f32_e32 v11, v8, v8
	v_lshlrev_b32_e32 v8, 16, v134
	v_fmac_f32_e32 v11, v8, v8
	v_and_b32_e32 v8, 0xffff0000, v134
	v_fmac_f32_e32 v11, v8, v8
	v_lshlrev_b32_e32 v8, 16, v135
	v_fmac_f32_e32 v11, v8, v8
	v_and_b32_e32 v8, 0xffff0000, v135
	v_fmac_f32_e32 v11, v8, v8
	v_lshlrev_b32_e32 v8, 16, v136
	v_fmac_f32_e32 v11, v8, v8
	v_and_b32_e32 v8, 0xffff0000, v136
	v_fmac_f32_e32 v11, v8, v8
	v_and_b32_e32 v9, 0xffff0000, v137
	v_lshlrev_b32_e32 v8, 16, v137
	v_pk_mul_f32 v[8:9], v[8:9], v[8:9]
	s_xor_b64 s[34:35], s[2:3], -1
	v_add_f32_e32 v8, v8, v11
	v_add_f32_e32 v11, v9, v8
	v_and_b32_e32 v9, 0xffff0000, v138
	v_lshlrev_b32_e32 v8, 16, v138
	v_pk_mul_f32 v[8:9], v[8:9], v[8:9]
	v_mad_i64_i32 v[2:3], s[2:3], v149, s88, 0
	v_add_f32_e32 v8, v8, v11
	v_add_f32_e32 v11, v9, v8
	v_and_b32_e32 v9, 0xffff0000, v139
	v_lshlrev_b32_e32 v8, 16, v139
	v_pk_mul_f32 v[8:9], v[8:9], v[8:9]
	v_mad_i64_i32 v[4:5], s[2:3], v151, s88, 0
	v_add_f32_e32 v8, v8, v11
	v_add_f32_e32 v8, v9, v8
	v_mov_b32_e32 v9, v8
	s_nop 1
	v_permlane32_swap_b32_e32 v8, v9
	v_add_f32_e32 v8, v8, v9
	v_mul_f32_e32 v9, 0x4f800000, v8
	v_cmp_gt_f32_e32 vcc, s91, v8
	v_mad_i64_i32 v[6:7], s[2:3], v153, s88, 0
	s_nop 0
	v_cndmask_b32_e32 v8, v8, v9, vcc
	v_sqrt_f32_e32 v9, v8
	s_add_i32 s2, s38, 0x100
	s_lshr_b32 s68, s2, 7
	v_mul_lo_u32 v178, v149, s53
	v_add_u32_e32 v11, -1, v9
	v_fma_f32 v12, -v11, v9, v8
	v_cmp_ge_f32_e64 s[2:3], 0, v12
; #define LAS __attribute__((address_space(3)))
; template <int DQK, int DV, bool CAUSAL, int KT, bool PRIO>
; DI void attn_unit(const bf16_t* Qb, int qpitch, const bf16_t* Kb, int kpitch, const bf16_t* Vtb, int vpitch, bf16_t* Ob, int opitch, int q0, int nt, LAS unsigned char* lds, float kbound, const float* qgain, const int* qpos, float qscale) {
;     ...
;     auto lstore = [&](int buf) {
; #pragma unroll
;         for (int i = 0; i < NKR; ++i) { const int c = tid + i * 512; if (NKC % 512 == 0 || c < NKC) *(LAS u32x4*)(lds + buf * KBUF + (c / KCH) * KS + (c % KCH) * 16) = kreg[i]; }
; #pragma unroll
;         for (int i = 0; i < NVR; ++i) { const int c = tid + i * 512; LAS unsigned char* p = lds + VOFF + buf * VBUF + (c / VCH) * VS + (c % VCH) * 16;
;             *(LAS u32x2*)p = (u32x2){vreg[i].x, vreg[i].y}; *(LAS u32x2*)(p + 8) = (u32x2){vreg[i].z, vreg[i].w}; }
;     };
;     ...
;         nomax = __all(sqrtf(q2) * kbound <= 100.0f) != 0;
;     }
;     lstore(0);
;     __syncthreads();
;     const int qabs = q0 + 32 * w + r, qlo = q0 + 32 * w;
	v_add_u32_e32 v12, 1, v9
	v_lshlrev_b32_e32 v179, 4, v150
	v_cndmask_b32_e64 v11, v9, v11, s[2:3]
	v_fma_f32 v9, -v12, v9, v8
	v_cmp_lt_f32_e64 s[2:3], 0, v9
	v_mul_lo_u32 v181, v151, s53
	v_lshlrev_b32_e32 v182, 4, v152
	v_cndmask_b32_e64 v9, v11, v12, s[2:3]
	v_mul_f32_e32 v11, 0x37800000, v9
	v_cndmask_b32_e32 v9, v9, v11, vcc
	v_cmp_class_f32_e32 vcc, v8, v176
	v_mul_lo_u32 v183, v153, s53
	v_lshlrev_b32_e32 v184, 4, v154
	v_cndmask_b32_e32 v8, v9, v8, vcc
	v_mul_f32_e32 v8, v174, v8
	v_cmp_ge_f32_e32 vcc, s52, v8
	v_add3_u32 v8, 0, v178, v179
	ds_write_b128 v8, v[96:99]
	v_add3_u32 v8, 0, v181, v182
	ds_write_b128 v8, v[100:103]
	v_add3_u32 v8, 0, v183, v184
	v_mul_lo_u32 v185, v68, s56
	ds_write_b128 v8, v[104:107]
	v_add_u32_e32 v8, 0, v185
	v_and_b32_e32 v186, 1, v69
	v_lshlrev_b32_e32 v186, 3, v186
	v_sub_u32_e32 v186, 0, v186
	v_lshl_add_u32 v186, v69, 4, v186
	v_add3_u32 v8, v8, v186, s57
	v_mul_lo_u32 v187, v74, s56
	ds_write2_b64 v8, v[108:109], v[110:111] offset1:2
	v_add_u32_e32 v8, 0, v187
	v_and_b32_e32 v188, 1, v75
	v_lshlrev_b32_e32 v188, 3, v188
	v_sub_u32_e32 v188, 0, v188
	v_lshl_add_u32 v188, v75, 4, v188
	v_and_b32_e32 v10, 31, v155
	v_add3_u32 v8, v8, v188, s57
	s_ashr_i32 s27, s26, 31
	s_and_b32 s69, s39, 0xffffffe0
	ds_write2_b64 v8, v[112:113], v[114:115] offset1:2
	v_mul_u32_u24_e32 v8, 0x110, v10
	s_cmp_lg_u64 vcc, exec
	v_add3_u32 v191, v0, v8, v0
	v_lshl_add_u64 v[8:9], s[22:23], 0, v[70:71]
	s_cselect_b64 s[2:3], -1, 0
	s_add_i32 s69, s69, s38
	v_lshl_add_u64 v[164:165], v[72:73], 1, v[8:9]
	v_lshl_add_u64 v[8:9], s[22:23], 0, v[64:65]
	v_lshl_add_u64 v[6:7], s[24:25], 0, v[6:7]
	v_lshl_add_u64 v[4:5], s[24:25], 0, v[4:5]
	v_lshl_add_u64 v[2:3], s[24:25], 0, v[2:3]
	v_mov_b32_e32 v14, v1
	v_mov_b32_e32 v15, v1
	v_or_b32_e32 v189, s69, v10
	v_mul_u32_u24_e32 v192, 0xd0, v10
	v_lshl_add_u64 v[166:167], v[66:67], 1, v[8:9]
	v_lshl_add_u64 v[168:169], v[62:63], 1, v[6:7]
	v_lshl_add_u64 v[170:171], v[60:61], 1, v[4:5]
	v_lshl_add_u64 v[172:173], v[58:59], 1, v[2:3]
	v_lshl_add_u64 v[164:165], s[4:5], 0, v[164:165]
	v_lshl_add_u64 v[166:167], s[4:5], 0, v[166:167]
	v_lshl_add_u64 v[168:169], s[4:5], 0, v[168:169]
	v_lshl_add_u64 v[170:171], s[4:5], 0, v[170:171]
	v_lshl_add_u64 v[172:173], s[4:5], 0, v[172:173]
	s_nop 0
	s_nop 0
	s_nop 0
	s_nop 0
	s_nop 0
	s_nop 0
	v_mov_b32_e32 v0, v1
	v_mov_b32_e32 v2, v1
	v_mov_b32_e32 v3, v1
	v_mov_b32_e32 v4, v1
	v_mov_b32_e32 v5, v1
	v_mov_b32_e32 v6, v1
	v_mov_b32_e32 v7, v1
	v_mov_b32_e32 v8, v1
	v_mov_b32_e32 v9, v1
	v_mov_b32_e32 v10, v1
	v_mov_b32_e32 v11, v1
	v_mov_b32_e32 v12, v1
	v_mov_b32_e32 v13, v1
	v_mov_b64_e32 v[30:31], v[14:15]
	v_mov_b64_e32 v[46:47], v[14:15]
	v_mov_b64_e32 v[62:63], v[14:15]
	s_mov_b32 s12, 0
	s_mov_b32 s98, 0
	s_or_b32 s70, s69, 31
	v_lshl_add_u32 v190, v148, 4, 0
	v_lshlrev_b32_e32 v180, 2, v148
	s_mov_b64 s[40:41], -1
	v_mov_b32_e32 v193, 0
	s_mov_b32 s71, 63
	v_mov_b64_e32 v[28:29], v[12:13]
	v_mov_b64_e32 v[26:27], v[10:11]
	v_mov_b64_e32 v[24:25], v[8:9]
	v_mov_b64_e32 v[22:23], v[6:7]
	v_mov_b64_e32 v[20:21], v[4:5]
	v_mov_b64_e32 v[18:19], v[2:3]
	v_mov_b64_e32 v[16:17], v[0:1]
	v_mov_b64_e32 v[44:45], v[12:13]
	v_mov_b64_e32 v[42:43], v[10:11]
	v_mov_b64_e32 v[40:41], v[8:9]
	v_mov_b64_e32 v[38:39], v[6:7]
	v_mov_b64_e32 v[36:37], v[4:5]
	v_mov_b64_e32 v[34:35], v[2:3]
	v_mov_b64_e32 v[32:33], v[0:1]
	v_mov_b64_e32 v[60:61], v[12:13]
	v_mov_b64_e32 v[58:59], v[10:11]
	v_mov_b64_e32 v[56:57], v[8:9]
	v_mov_b64_e32 v[54:55], v[6:7]
	v_mov_b64_e32 v[52:53], v[4:5]
	v_mov_b64_e32 v[50:51], v[2:3]
	v_mov_b64_e32 v[48:49], v[0:1]
	v_mov_b32_e32 v0, 0
	s_waitcnt lgkmcnt(0)
	s_barrier

; #define MFMA32(a, b, c) __builtin_amdgcn_mfma_f32_32x32x16_bf16((a), (b), (c), 0, 0, 0)
; template <int DQK, int DV, bool CAUSAL, int KT, bool PRIO>
; DI void attn_unit(const bf16_t* Qb, int qpitch, const bf16_t* Kb, int kpitch, const bf16_t* Vtb, int vpitch, bf16_t* Ob, int opitch, int q0, int nt, LAS unsigned char* lds, float kbound, const float* qgain, const int* qpos, float qscale) {
;     ...
;     for (int kt = 0; kt < nt; ++kt) {
;         const int buf = kt & 1;
;         if (kt + 1 < nt) gload(kt + 1);
; #pragma unroll
;         for (int hf = 0; hf < KT / 64; ++hf) {
;             const int key0 = kt * KT + 64 * hf;
;             if (!CAUSAL || key0 <= qlo + 31) {
;     ...
;                     for (int q4 = 0; q4 < 4; ++q4)
; #pragma unroll
;                         for (int d = 0; d < NDB; ++d) o[d] = MFMA32(vf[q4][d], pf[q4], o[d]);
;                     __builtin_amdgcn_sched_barrier(0); __builtin_amdgcn_s_setprio(0); __builtin_amdgcn_sched_barrier(0);
.LBB0_1489:
	s_and_b32 s75, s12, 1
	s_mul_i32 s13, s75, 0x6800
	v_add_u32_e32 v250, s13, v190
	s_mul_i32 s13, s75, 0x4400
	s_sub_i32 s12, s71, 63
	v_add_u32_e32 v194, v250, v192
	v_add_u32_e32 v250, s13, v191
	s_cmp_gt_i32 s12, s70
	v_add_u32_e32 v14, 0xd000, v250
	v_add_u32_e32 v15, 0xf200, v250
	s_cbranch_scc0 .LBB0_1495
	global_load_dwordx4 v[96:99], v[172:173], off
	global_load_dwordx4 v[100:103], v[170:171], off
	global_load_dwordx4 v[104:107], v[168:169], off
	global_load_dwordx4 v[108:111], v[166:167], off
	global_load_dwordx4 v[112:115], v[164:165], off
	v_lshl_add_u64 v[164:165], v[164:165], 0, s[14:15]
	v_lshl_add_u64 v[166:167], v[166:167], 0, s[14:15]
	v_lshl_add_u64 v[168:169], v[168:169], 0, s[16:17]
	v_lshl_add_u64 v[170:171], v[170:171], 0, s[16:17]
	v_lshl_add_u64 v[172:173], v[172:173], 0, s[16:17]
	s_cmp_eq_u32 s98, 0
	s_cbranch_scc1 .Lmla_dpvb
	s_setprio 1
	v_mfma_f32_32x32x16_bf16 v[32:47], v[156:159], v[64:67], v[32:47]
	v_mfma_f32_32x32x16_bf16 v[16:31], v[152:155], v[64:67], v[16:31]
	v_mfma_f32_32x32x16_bf16 v[32:47], v[140:143], v[72:75], v[32:47]
	v_mfma_f32_32x32x16_bf16 v[16:31], v[148:151], v[72:75], v[16:31]
	v_mfma_f32_32x32x16_bf16 v[32:47], v[144:147], v[68:71], v[32:47]
	v_mfma_f32_32x32x16_bf16 v[16:31], v[10:13], v[68:71], v[16:31]
	v_mfma_f32_32x32x16_bf16 v[32:47], v[6:9], v[76:79], v[32:47]
	v_mfma_f32_32x32x16_bf16 v[16:31], v[2:5], v[76:79], v[16:31]
	s_setprio 0
	s_mov_b32 s98, 0
.Lmla_dpvb:
	s_add_i32 s12, s71, 1
	s_cmp_gt_i32 s12, s70
	s_cbranch_scc0 .Lmla_b1_pre

; #define LAS __attribute__((address_space(3)))
; #define MFMA32(a, b, c) __builtin_amdgcn_mfma_f32_32x32x16_bf16((a), (b), (c), 0, 0, 0)
; template <int DQK, int DV, bool CAUSAL, int KT, bool PRIO>
; DI void attn_unit(const bf16_t* Qb, int qpitch, const bf16_t* Kb, int kpitch, const bf16_t* Vtb, int vpitch, bf16_t* Ob, int opitch, int q0, int nt, LAS unsigned char* lds, float kbound, const float* qgain, const int* qpos, float qscale) {
;     ...
;                 if (PRIO) {
;                     constexpr int KSN = DQK / 16, NDB = DV / 32;
;                     f32x16 s0 = negm, s1 = negm;
;                     const LAS unsigned char* kb = lds + buf * KBUF + (64 * hf + r) * KS + h * 16;
;                     const LAS unsigned char* vb = lds + VOFF + buf * VBUF + r * VS + h * 8 + 128 * hf;
;                     bf16x8 kf0[KSN], kf1[KSN], vf[4][NDB];
; #pragma unroll
;                     for (int ks = 0; ks < KSN; ++ks) { kf0[ks] = *(const LAS bf16x8*)(kb + ks * 32); kf1[ks] = *(const LAS bf16x8*)(kb + 32 * KS + ks * 32); }
;                     __builtin_amdgcn_sched_barrier(0); __builtin_amdgcn_s_setprio(1); __builtin_amdgcn_sched_barrier(0);
; #pragma unroll
;                     for (int ks = 0; ks < KSN; ++ks) { s0 = MFMA32(kf0[ks], qf[ks], s0); s1 = MFMA32(kf1[ks], qf[ks], s1); }
;                     __builtin_amdgcn_sched_barrier(0); __builtin_amdgcn_s_setprio(0); __builtin_amdgcn_sched_barrier(0);
; #pragma unroll
;                     for (int q4 = 0; q4 < 4; ++q4)
; #pragma unroll
;                         for (int d = 0; d < NDB; ++d) { const LAS unsigned char* vp = vb + d * 32 * VS + q4 * 32;
;                             const s16x4 lo = *(const LAS s16x4*)vp, hi = *(const LAS s16x4*)(vp + 16); vf[q4][d] = (bf16x8){lo[0], lo[1], lo[2], lo[3], hi[0], hi[1], hi[2], hi[3]}; }
;                     if (CAUSAL && key0 + 63 > qlo) {
; #pragma unroll
;                         for (int i = 0; i < 16; ++i) { const int key = key0 + (i & 3) + 8 * (i >> 2) + 4 * h; if (key > qabs) s0[i] = -1e30f; if (key + 32 > qabs) s1[i] = -1e30f; }
;     ...
;                     for (int q4 = 0; q4 < 4; ++q4)
; #pragma unroll
;                         for (int d = 0; d < NDB; ++d) o[d] = MFMA32(vf[q4][d], pf[q4], o[d]);
;                     __builtin_amdgcn_sched_barrier(0); __builtin_amdgcn_s_setprio(0); __builtin_amdgcn_sched_barrier(0);
.LBB0_1495:
	ds_read_b128 v[214:217], v194
	ds_read_b128 v[218:221], v194 offset:32
	ds_read_b128 v[222:225], v194 offset:6656
	ds_read_b128 v[226:229], v194 offset:6688
	ds_read_b128 v[230:233], v194 offset:64
	ds_read_b128 v[234:237], v194 offset:96
	ds_read_b128 v[238:241], v194 offset:6720
	ds_read_b128 v[242:245], v194 offset:6752
	ds_read_b128 v[198:201], v194 offset:128
	ds_read_b128 v[202:205], v194 offset:160
	ds_read_b128 v[206:209], v194 offset:6784
	ds_read_b128 v[210:213], v194 offset:6816
	global_load_dwordx4 v[96:99], v[172:173], off
	global_load_dwordx4 v[100:103], v[170:171], off
	global_load_dwordx4 v[104:107], v[168:169], off
	global_load_dwordx4 v[108:111], v[166:167], off
	global_load_dwordx4 v[112:115], v[164:165], off
	v_lshl_add_u64 v[164:165], v[164:165], 0, s[14:15]
	v_lshl_add_u64 v[166:167], v[166:167], 0, s[14:15]
	v_lshl_add_u64 v[168:169], v[168:169], 0, s[16:17]
	v_lshl_add_u64 v[170:171], v[170:171], 0, s[16:17]
	v_lshl_add_u64 v[172:173], v[172:173], 0, s[16:17]
	s_cmp_eq_u32 s98, 0
	s_cbranch_scc1 .Lmla_dpva
	s_setprio 1
	v_mfma_f32_32x32x16_bf16 v[32:47], v[156:159], v[64:67], v[32:47]
	v_mfma_f32_32x32x16_bf16 v[16:31], v[152:155], v[64:67], v[16:31]
	v_mfma_f32_32x32x16_bf16 v[32:47], v[140:143], v[72:75], v[32:47]
	v_mfma_f32_32x32x16_bf16 v[16:31], v[148:151], v[72:75], v[16:31]
	v_mfma_f32_32x32x16_bf16 v[32:47], v[144:147], v[68:71], v[32:47]
	v_mfma_f32_32x32x16_bf16 v[16:31], v[10:13], v[68:71], v[16:31]
	v_mfma_f32_32x32x16_bf16 v[32:47], v[6:9], v[76:79], v[32:47]
	v_mfma_f32_32x32x16_bf16 v[16:31], v[2:5], v[76:79], v[16:31]
	s_setprio 0
	s_mov_b32 s98, 0
.Lmla_dpva:
	s_setprio 1
	s_setprio 0
	s_waitcnt lgkmcnt(0)
	v_mfma_f32_32x32x16_bf16 v[80:95], v[214:217], v[116:119], v[48:63]
	s_cmp_le_i32 s71, s69
	v_mfma_f32_32x32x16_bf16 v[64:79], v[222:225], v[116:119], v[48:63]
	v_mfma_f32_32x32x16_bf16 v[80:95], v[218:221], v[120:123], v[80:95]
	v_mfma_f32_32x32x16_bf16 v[64:79], v[226:229], v[120:123], v[64:79]
	v_mfma_f32_32x32x16_bf16 v[80:95], v[230:233], v[124:127], v[80:95]
	v_mfma_f32_32x32x16_bf16 v[64:79], v[238:241], v[124:127], v[64:79]
	ds_read_b128 v[152:155], v14
	ds_read_b128 v[140:143], v14 offset:32
	v_mfma_f32_32x32x16_bf16 v[80:95], v[234:237], v[128:131], v[80:95]
	v_mfma_f32_32x32x16_bf16 v[64:79], v[242:245], v[128:131], v[64:79]
	ds_read_b128 v[156:159], v15
	ds_read_b128 v[148:151], v15 offset:32
	ds_read_b128 v[144:147], v14 offset:64
	ds_read_b128 v[10:13], v15 offset:64
	ds_read_b128 v[6:9], v14 offset:96
	ds_read_b128 v[2:5], v15 offset:96
	v_mfma_f32_32x32x16_bf16 v[80:95], v[198:201], v[132:135], v[80:95]
	v_mfma_f32_32x32x16_bf16 v[64:79], v[206:209], v[132:135], v[64:79]
	v_mfma_f32_32x32x16_bf16 v[80:95], v[202:205], v[136:139], v[80:95]
	v_mfma_f32_32x32x16_bf16 v[64:79], v[210:213], v[136:139], v[64:79]
	ds_read_b128 v[214:217], v194 offset:13312
	ds_read_b128 v[218:221], v194 offset:13344
	ds_read_b128 v[222:225], v194 offset:19968
	ds_read_b128 v[226:229], v194 offset:20000
	ds_read_b128 v[230:233], v194 offset:13376
	ds_read_b128 v[234:237], v194 offset:13408
	ds_read_b128 v[238:241], v194 offset:20032
	ds_read_b128 v[242:245], v194 offset:20064
	s_cbranch_scc1 .LBB0_1497
	v_add_u32_e32 v195, s71, v180
	v_subrev_u32_e32 v198, 31, v195
	v_subrev_u32_e32 v197, 63, v195
	v_cmp_le_i32_e32 vcc, v198, v189
	s_nop 6
	v_cndmask_b32_e32 v64, v177, v64, vcc
	v_cmp_lt_i32_e32 vcc, v197, v189
	s_nop 1
	v_cndmask_b32_e32 v81, v177, v81, vcc
	v_cmp_le_i32_e32 vcc, v197, v189
	v_subrev_u32_e32 v197, 30, v195
	s_nop 0
	v_cndmask_b32_e32 v80, v177, v80, vcc
	v_cmp_le_i32_e32 vcc, v197, v189
	v_subrev_u32_e32 v197, 61, v195
	s_nop 0
	v_cndmask_b32_e32 v65, v177, v65, vcc
	v_cmp_le_i32_e32 vcc, v197, v189
	v_subrev_u32_e32 v197, 29, v195
	s_nop 0
	v_cndmask_b32_e32 v82, v177, v82, vcc
	v_cmp_le_i32_e32 vcc, v197, v189
	v_subrev_u32_e32 v197, 60, v195
	s_nop 0
	v_cndmask_b32_e32 v66, v177, v66, vcc
	v_cmp_le_i32_e32 vcc, v197, v189
	v_subrev_u32_e32 v197, 28, v195
	s_nop 0
	v_cndmask_b32_e32 v83, v177, v83, vcc
	v_cmp_le_i32_e32 vcc, v197, v189
	v_subrev_u32_e32 v197, 55, v195
	s_nop 0
	v_cndmask_b32_e32 v67, v177, v67, vcc
	v_cmp_le_i32_e32 vcc, v197, v189
	v_subrev_u32_e32 v197, 23, v195
	s_nop 0
	v_cndmask_b32_e32 v84, v177, v84, vcc
	v_cmp_le_i32_e32 vcc, v197, v189
	v_subrev_u32_e32 v197, 54, v195
	s_nop 0
	v_cndmask_b32_e32 v68, v177, v68, vcc
	v_cmp_le_i32_e32 vcc, v197, v189
	v_subrev_u32_e32 v197, 22, v195
	s_nop 0
	v_cndmask_b32_e32 v85, v177, v85, vcc
	v_cmp_le_i32_e32 vcc, v197, v189
	v_subrev_u32_e32 v197, 53, v195
	s_nop 0
	v_cndmask_b32_e32 v69, v177, v69, vcc
	v_cmp_le_i32_e32 vcc, v197, v189
	v_subrev_u32_e32 v197, 21, v195
	s_nop 0
	v_cndmask_b32_e32 v86, v177, v86, vcc
	v_cmp_le_i32_e32 vcc, v197, v189
	v_subrev_u32_e32 v197, 52, v195
	s_nop 0
	v_cndmask_b32_e32 v70, v177, v70, vcc
	v_cmp_le_i32_e32 vcc, v197, v189
	v_subrev_u32_e32 v197, 20, v195
	s_nop 0
	v_cndmask_b32_e32 v87, v177, v87, vcc
	v_cmp_le_i32_e32 vcc, v197, v189
	v_subrev_u32_e32 v197, 47, v195
	s_nop 0
	v_cndmask_b32_e32 v71, v177, v71, vcc
	v_cmp_le_i32_e32 vcc, v197, v189
	v_add_u32_e32 v197, -15, v195
	s_nop 0
	v_cndmask_b32_e32 v88, v177, v88, vcc
	v_cmp_le_i32_e32 vcc, v197, v189
	v_subrev_u32_e32 v197, 46, v195
	s_nop 0
	v_cndmask_b32_e32 v72, v177, v72, vcc
	v_cmp_le_i32_e32 vcc, v197, v189
	v_add_u32_e32 v197, -14, v195
	s_nop 0
	v_cndmask_b32_e32 v89, v177, v89, vcc
	v_cmp_le_i32_e32 vcc, v197, v189
	v_subrev_u32_e32 v197, 45, v195
	s_nop 0
	v_cndmask_b32_e32 v73, v177, v73, vcc
	v_cmp_le_i32_e32 vcc, v197, v189
	v_add_u32_e32 v197, -13, v195
	s_nop 0
	v_cndmask_b32_e32 v90, v177, v90, vcc
	v_cmp_le_i32_e32 vcc, v197, v189
	v_subrev_u32_e32 v197, 44, v195
	s_nop 0
	v_cndmask_b32_e32 v74, v177, v74, vcc
	v_cmp_le_i32_e32 vcc, v197, v189
	v_add_u32_e32 v197, -12, v195
	s_nop 0
	v_cndmask_b32_e32 v91, v177, v91, vcc
	v_cmp_le_i32_e32 vcc, v197, v189
	v_subrev_u32_e32 v197, 39, v195
	s_nop 0
	v_cndmask_b32_e32 v75, v177, v75, vcc
	v_cmp_le_i32_e32 vcc, v197, v189
	v_add_u32_e32 v197, -7, v195
	s_nop 0
	v_cndmask_b32_e32 v92, v177, v92, vcc
	v_cmp_le_i32_e32 vcc, v197, v189
	v_subrev_u32_e32 v197, 38, v195
	s_nop 0
	v_cndmask_b32_e32 v76, v177, v76, vcc
	v_cmp_le_i32_e32 vcc, v197, v189
	v_add_u32_e32 v197, -6, v195
	s_nop 0
	v_cndmask_b32_e32 v93, v177, v93, vcc
	v_cmp_le_i32_e32 vcc, v197, v189
	v_subrev_u32_e32 v197, 37, v195
	s_nop 0
	v_cndmask_b32_e32 v77, v177, v77, vcc
	v_cmp_le_i32_e32 vcc, v197, v189
	v_add_u32_e32 v197, -5, v195
	s_nop 0
	v_cndmask_b32_e32 v94, v177, v94, vcc
	v_cmp_le_i32_e32 vcc, v197, v189
	v_subrev_u32_e32 v197, 36, v195
	v_add_u32_e32 v195, -4, v195
	v_cndmask_b32_e32 v78, v177, v78, vcc
	v_cmp_le_i32_e32 vcc, v197, v189
	s_nop 1
	v_cndmask_b32_e32 v95, v177, v95, vcc
	v_cmp_le_i32_e32 vcc, v195, v189
	s_nop 1
	v_cndmask_b32_e32 v79, v177, v79, vcc

; #define LAS __attribute__((address_space(3)))
; DI unsigned pk2(float lo, float hi) { typedef float v2f __attribute__((ext_vector_type(2))); typedef __bf16 v2b __attribute__((ext_vector_type(2))); v2f v = {lo, hi}; v2b b = __builtin_convertvector(v, v2b); return __builtin_bit_cast(unsigned, b); }
; template <int DQK, int DV, bool CAUSAL, int KT, bool PRIO>
; DI void attn_unit(const bf16_t* Qb, int qpitch, const bf16_t* Kb, int kpitch, const bf16_t* Vtb, int vpitch, bf16_t* Ob, int opitch, int q0, int nt, LAS unsigned char* lds, float kbound, const float* qgain, const int* qpos, float qscale) {
;     ...
;     auto lstore = [&](int buf) {
; #pragma unroll
;         for (int i = 0; i < NKR; ++i) { const int c = tid + i * 512; if (NKC % 512 == 0 || c < NKC) *(LAS u32x4*)(lds + buf * KBUF + (c / KCH) * KS + (c % KCH) * 16) = kreg[i]; }
; #pragma unroll
;         for (int i = 0; i < NVR; ++i) { const int c = tid + i * 512; LAS unsigned char* p = lds + VOFF + buf * VBUF + (c / VCH) * VS + (c % VCH) * 16;
;             *(LAS u32x2*)p = (u32x2){vreg[i].x, vreg[i].y}; *(LAS u32x2*)(p + 8) = (u32x2){vreg[i].z, vreg[i].w}; }
;     };
;     ...
;                     float ps = 0.f;
; #pragma unroll
;                     for (int i = 0; i < 16; ++i) { s0[i] = __builtin_amdgcn_exp2f(s0[i]); ps += s0[i]; asm volatile("" : "+v"(ps)); }
; #pragma unroll
;                     for (int i = 0; i < 16; ++i) { s1[i] = __builtin_amdgcn_exp2f(s1[i]); ps += s1[i]; asm volatile("" : "+v"(ps)); }
;                     lrun += ps;
;                     bf16x8 pf[4];
; #pragma unroll
;                     for (int sf = 0; sf < 2; ++sf) {
;                         u32x4 pw; pw.x = pk2(s0[8 * sf], s0[8 * sf + 1]); pw.y = pk2(s0[8 * sf + 2], s0[8 * sf + 3]); pw.z = pk2(s0[8 * sf + 4], s0[8 * sf + 5]); pw.w = pk2(s0[8 * sf + 6], s0[8 * sf + 7]); pf[sf] = __builtin_bit_cast(bf16x8, pw);
;                         u32x4 pv; pv.x = pk2(s1[8 * sf], s1[8 * sf + 1]); pv.y = pk2(s1[8 * sf + 2], s1[8 * sf + 3]); pv.z = pk2(s1[8 * sf + 4], s1[8 * sf + 5]); pv.w = pk2(s1[8 * sf + 6], s1[8 * sf + 7]); pf[2 + sf] = __builtin_bit_cast(bf16x8, pv);
;                     }
.LBB0_1514:
	s_nop 7
	v_exp_f32_e32 v14, v80
	v_exp_f32_e32 v15, v81
	v_exp_f32_e32 v80, v82
	v_exp_f32_e32 v81, v83
	v_add_f32_e32 v82, 0, v14
	v_exp_f32_e32 v83, v84
	v_add_f32_e32 v82, v15, v82
	v_exp_f32_e32 v84, v85
	v_add_f32_e32 v82, v80, v82
	v_exp_f32_e32 v85, v86
	v_add_f32_e32 v82, v81, v82
	v_exp_f32_e32 v86, v87
	v_add_f32_e32 v82, v83, v82
	v_exp_f32_e32 v87, v88
	v_add_f32_e32 v82, v84, v82
	v_exp_f32_e32 v88, v89
	v_add_f32_e32 v82, v85, v82
	v_exp_f32_e32 v89, v90
	v_add_f32_e32 v82, v86, v82
	v_exp_f32_e32 v90, v91
	v_add_f32_e32 v82, v87, v82
	v_exp_f32_e32 v91, v92
	v_add_f32_e32 v82, v88, v82
	v_exp_f32_e32 v92, v93
	v_add_f32_e32 v82, v89, v82
	v_exp_f32_e32 v93, v94
	v_add_f32_e32 v82, v90, v82
	v_exp_f32_e32 v94, v95
	v_add_f32_e32 v82, v91, v82
	v_exp_f32_e32 v95, v64
	v_add_f32_e32 v82, v92, v82
	v_exp_f32_e32 v194, v66
	v_add_f32_e32 v82, v93, v82
	v_exp_f32_e32 v195, v67
	v_add_f32_e32 v64, v94, v82
	v_exp_f32_e32 v82, v65
	v_exp_f32_e32 v197, v68
	v_add_f32_e32 v64, v95, v64
	v_exp_f32_e32 v198, v69
	v_add_f32_e32 v64, v82, v64
	v_exp_f32_e32 v199, v70
	v_add_f32_e32 v64, v194, v64
	v_exp_f32_e32 v71, v71
	v_add_f32_e32 v64, v195, v64
	v_exp_f32_e32 v200, v72
	v_add_f32_e32 v64, v197, v64
	v_exp_f32_e32 v201, v73
	v_add_f32_e32 v64, v198, v64
	v_exp_f32_e32 v202, v74
	v_add_f32_e32 v64, v199, v64
	v_exp_f32_e32 v203, v75
	v_add_f32_e32 v64, v71, v64
	v_exp_f32_e32 v204, v76
	v_add_f32_e32 v64, v200, v64
	v_exp_f32_e32 v205, v77
	v_add_f32_e32 v64, v201, v64
	v_exp_f32_e32 v206, v78
	v_add_f32_e32 v64, v202, v64
	v_exp_f32_e32 v79, v79
	v_add_f32_e32 v64, v203, v64
	v_cvt_pk_bf16_f32 v65, v80, v81
	v_add_f32_e32 v64, v204, v64
	v_cvt_pk_bf16_f32 v66, v83, v84
	v_add_f32_e32 v64, v205, v64
	v_cvt_pk_bf16_f32 v67, v85, v86
	v_add_f32_e32 v64, v206, v64
	v_cvt_pk_bf16_f32 v68, v95, v82
	v_add_f32_e32 v207, v79, v64
	v_cvt_pk_bf16_f32 v64, v14, v15
	v_cvt_pk_bf16_f32 v69, v194, v195
	v_cvt_pk_bf16_f32 v70, v197, v198
	v_cvt_pk_bf16_f32 v71, v199, v71
	v_cvt_pk_bf16_f32 v72, v87, v88
	v_cvt_pk_bf16_f32 v73, v89, v90
	v_cvt_pk_bf16_f32 v74, v91, v92
	v_cvt_pk_bf16_f32 v75, v93, v94
	v_cvt_pk_bf16_f32 v76, v200, v201
	v_cvt_pk_bf16_f32 v77, v202, v203
	v_cvt_pk_bf16_f32 v78, v204, v205
	v_cvt_pk_bf16_f32 v79, v206, v79
	s_xor_b32 s100, s75, 1
	s_mul_i32 s101, s100, 0x6800
	v_add3_u32 v250, s101, v178, v179
	s_waitcnt vmcnt(0)
	ds_write_b128 v250, v[96:99]
	v_add3_u32 v251, s101, v181, v182
	s_mulk_i32 s100, 0xdc00
	ds_write_b128 v251, v[100:103]
	v_add3_u32 v250, s101, v183, v184
	s_add_i32 s101, s101, s100
	ds_write_b128 v250, v[104:107]
	v_add_u32_e32 v251, s101, v185
	v_add3_u32 v251, v251, v186, s57
	ds_write2_b64 v251, v[108:109], v[110:111] offset1:2
	v_add_u32_e32 v250, s101, v187
	v_add3_u32 v250, v250, v188, s57
	ds_write2_b64 v250, v[112:113], v[114:115] offset1:2
	s_mov_b32 s98, 1
	v_add_f32_e32 v0, v0, v207
	s_branch .LBB0_1493
	s_nop 0
	s_nop 0
	s_nop 0
	s_nop 0
	s_nop 0
	s_nop 0
	s_nop 0
	s_nop 0
	s_nop 0
	s_nop 0
	s_nop 0
	s_nop 0
	s_nop 0
